# prep conv-mixer loop: halo loads (previous one/two tokens + taps) issued unconditionally together with the main loads instead of inside two conditional blocks each behind a full wait
# baseline (speedup 1.0000x reference)
; __device__ __forceinline__ void phase_prep(const Params& p, int l) {
;     ...
;   for (size_t e = gt; e < (size_t)T_TOK * 64; e += nth) {
;     const int t = (int)(e >> 6), c0 = (int)(e & 63) * 8;
;     const int s = t & (SEQL - 1);
;     float w0[8], w1[8], w2[8], bb[8], cv[8], xv[8], acc[8];
;     load8f(p.convw + (l * 3 + 0) * 512 + c0, w0);
;     load8f(p.convw + (l * 3 + 1) * 512 + c0, w1);
;     load8f(p.convw + (l * 3 + 2) * 512 + c0, w2);
;     const u16* r2 = Uc + (size_t)t * 1536 + c0;
;     unpack8(*(const uint4*)(r2), bb);
;     unpack8(*(const uint4*)(r2 + 512), cv);
;     unpack8(*(const uint4*)(r2 + 1024), xv);
; #pragma unroll
;     for (int j = 0; j < 8; ++j) acc[j] = w2[j] * (cv[j] * xv[j]);
;     if (s >= 1) {
;       unpack8(*(const uint4*)(r2 - 1536 + 512), cv);
;       unpack8(*(const uint4*)(r2 - 1536 + 1024), xv);
; #pragma unroll
;       for (int j = 0; j < 8; ++j) acc[j] += w1[j] * (cv[j] * xv[j]);
;     }
;     if (s >= 2) {
;       unpack8(*(const uint4*)(r2 - 3072 + 512), cv);
;       unpack8(*(const uint4*)(r2 - 3072 + 1024), xv);
; #pragma unroll
;       for (int j = 0; j < 8; ++j) acc[j] += w0[j] * (cv[j] * xv[j]);
;     }
; #pragma unroll
;     for (int j = 0; j < 8; ++j) acc[j] *= bb[j];
;     *(uint4*)(Y + (size_t)t * 1536 + c0) = pack8(acc);
;   }
.LBB0_397:
	v_alignbit_b32 v33, v19, v18, 6
	v_mad_u64_u32 v[20:21], s[10:11], v33, s97, 0
	v_mov_b32_e32 v0, v21
	v_lshrrev_b32_e32 v2, 6, v19
	v_mad_u64_u32 v[2:3], s[10:11], v2, s97, v[0:1]
	v_readlane_b32 s10, v252, 46
	v_and_b32_e32 v4, 0x1f8, v16
	v_mov_b32_e32 v21, v2
	v_readlane_b32 s11, v252, 47
	v_lshlrev_b32_e32 v0, 1, v4
	v_lshlrev_b32_e32 v32, 2, v4
	v_lshl_add_u64 v[2:3], v[20:21], 1, s[10:11]
	v_lshl_add_u64 v[30:31], v[2:3], 0, v[0:1]
	global_load_dwordx4 v[22:25], v[30:31], off offset:1024
	global_load_dwordx4 v[26:29], v[30:31], off offset:2048
	global_load_dwordx4 v[36:39], v32, s[36:37]
	global_load_dwordx4 v[40:43], v32, s[36:37] offset:16
	global_load_dwordx4 v[6:9], v32, s[22:23] offset:16
	global_load_dwordx4 v[10:13], v32, s[22:23]
	global_load_dwordx4 v[2:5], v[30:31], off
	global_load_dwordx4 v[80:83], v[30:31], off offset:-2048
	global_load_dwordx4 v[84:87], v[30:31], off offset:-1024
	v_mov_b32_e32 v104, v32
	v_mov_b32_e32 v105, v1
	v_lshl_add_u64 v[104:105], s[22:23], 0, v[104:105]
	global_load_dwordx4 v[88:91], v[104:105], off offset:2048
	global_load_dwordx4 v[92:95], v[104:105], off offset:2064
	global_load_dwordx4 v[96:99], v[30:31], off offset:-4096
	v_add_co_u32_e32 v106, vcc, 0xfffff000, v30
	s_nop 1
	v_addc_co_u32_e32 v107, vcc, -1, v31, vcc
	global_load_dwordx4 v[100:103], v[106:107], off offset:-1024
	v_and_b32_e32 v35, 0x1fff, v33
	v_cmp_ne_u32_e32 vcc, 0, v35
	s_waitcnt vmcnt(12)
	v_lshlrev_b32_e32 v44, 16, v22
	v_lshlrev_b32_e32 v46, 16, v23
	v_lshlrev_b32_e32 v50, 16, v24
	v_lshlrev_b32_e32 v52, 16, v25
	s_waitcnt vmcnt(11)
	v_lshlrev_b32_e32 v54, 16, v26
	v_lshlrev_b32_e32 v56, 16, v27
	v_lshlrev_b32_e32 v58, 16, v28
	v_lshlrev_b32_e32 v60, 16, v29
	v_and_b32_e32 v55, 0xffff0000, v26
	v_and_b32_e32 v45, 0xffff0000, v22
	v_and_b32_e32 v57, 0xffff0000, v27
	v_and_b32_e32 v47, 0xffff0000, v23
	v_and_b32_e32 v59, 0xffff0000, v28
	v_and_b32_e32 v51, 0xffff0000, v24
	v_and_b32_e32 v61, 0xffff0000, v29
	v_and_b32_e32 v53, 0xffff0000, v25
	v_pk_mul_f32 v[22:23], v[44:45], v[54:55]
	v_pk_mul_f32 v[24:25], v[46:47], v[56:57]
	v_pk_mul_f32 v[26:27], v[50:51], v[58:59]
	v_pk_mul_f32 v[28:29], v[52:53], v[60:61]
	s_waitcnt vmcnt(10)
	v_pk_mul_f32 v[22:23], v[36:37], v[22:23]
	v_pk_mul_f32 v[24:25], v[38:39], v[24:25]
	s_waitcnt vmcnt(9)
	v_pk_mul_f32 v[26:27], v[40:41], v[26:27]
	v_pk_mul_f32 v[28:29], v[42:43], v[28:29]
	s_and_saveexec_b64 s[40:41], vcc
	s_cbranch_execz .LBB0_399
	s_waitcnt vmcnt(5)
	v_lshlrev_b32_e32 v32, 16, v80
	v_lshlrev_b32_e32 v54, 16, v81
	v_lshlrev_b32_e32 v56, 16, v82
	v_lshlrev_b32_e32 v58, 16, v83
	s_waitcnt vmcnt(4)
	v_lshlrev_b32_e32 v60, 16, v84
	v_lshlrev_b32_e32 v62, 16, v85
	v_lshlrev_b32_e32 v64, 16, v86
	v_lshlrev_b32_e32 v66, 16, v87
	v_and_b32_e32 v61, 0xffff0000, v84
	v_and_b32_e32 v33, 0xffff0000, v80
	v_and_b32_e32 v63, 0xffff0000, v85
	v_and_b32_e32 v55, 0xffff0000, v81
	v_and_b32_e32 v65, 0xffff0000, v86
	v_and_b32_e32 v57, 0xffff0000, v82
	v_and_b32_e32 v67, 0xffff0000, v87
	v_and_b32_e32 v59, 0xffff0000, v83
	v_pk_mul_f32 v[32:33], v[32:33], v[60:61]
	v_pk_mul_f32 v[36:37], v[54:55], v[62:63]
	v_pk_mul_f32 v[38:39], v[56:57], v[64:65]
	v_pk_mul_f32 v[40:41], v[58:59], v[66:67]
	s_waitcnt vmcnt(3)
	v_pk_fma_f32 v[22:23], v[88:89], v[32:33], v[22:23]
	v_pk_fma_f32 v[24:25], v[90:91], v[36:37], v[24:25]
	s_waitcnt vmcnt(2)
	v_pk_fma_f32 v[26:27], v[92:93], v[38:39], v[26:27]
	v_pk_fma_f32 v[28:29], v[94:95], v[40:41], v[28:29]
.LBB0_399:
	s_or_b64 exec, exec, s[40:41]
	v_cmp_lt_u32_e32 vcc, 1, v35
	s_and_saveexec_b64 s[40:41], vcc
	s_cbranch_execz .LBB0_396
	s_waitcnt vmcnt(1)
	v_lshlrev_b32_e32 v40, 16, v96
	v_lshlrev_b32_e32 v42, 16, v97
	v_lshlrev_b32_e32 v44, 16, v98
	v_lshlrev_b32_e32 v46, 16, v99
	v_and_b32_e32 v41, 0xffff0000, v96
	v_and_b32_e32 v43, 0xffff0000, v97
	v_and_b32_e32 v45, 0xffff0000, v98
	v_and_b32_e32 v47, 0xffff0000, v99
	s_waitcnt vmcnt(0)
	v_lshlrev_b32_e32 v36, 16, v100
	v_lshlrev_b32_e32 v38, 16, v101
	v_lshlrev_b32_e32 v50, 16, v102
	v_lshlrev_b32_e32 v52, 16, v103
	v_and_b32_e32 v37, 0xffff0000, v100
	v_and_b32_e32 v39, 0xffff0000, v101
	v_and_b32_e32 v51, 0xffff0000, v102
	v_and_b32_e32 v53, 0xffff0000, v103
	v_pk_mul_f32 v[30:31], v[36:37], v[40:41]
	v_pk_mul_f32 v[32:33], v[38:39], v[42:43]
	v_pk_mul_f32 v[36:37], v[50:51], v[44:45]
	v_pk_mul_f32 v[38:39], v[52:53], v[46:47]
	v_pk_fma_f32 v[22:23], v[10:11], v[30:31], v[22:23]
	v_pk_fma_f32 v[24:25], v[12:13], v[32:33], v[24:25]
	v_pk_fma_f32 v[26:27], v[6:7], v[36:37], v[26:27]
	v_pk_fma_f32 v[28:29], v[8:9], v[38:39], v[28:29]
	s_branch .LBB0_396
